# GEMM K-loops: priority 1 held across both 16-MFMA blocks of a super-phase (the s_setprio 0 / s_setprio 1 pair between them removed)
# speedup vs baseline: 1.0025x; 1.0025x over previous
.LBB0_152:
	s_add_u32 s66, s40, 0xfffc0080
	s_addc_u32 s67, s41, -1
	s_add_i32 s84, 0, 0x10000
	s_cmp_eq_u32 s83, 12
	s_cselect_b32 s73, s56, s67
	s_cselect_b32 s72, s57, s66
	v_add_u32_e32 v154, s84, v157
	s_cselect_b32 s67, s55, s82
	s_cselect_b32 s66, s80, s81
	s_add_i32 s87, 0, 0x14000
	ds_read_b128 v[162:165], v154
	ds_read_b128 v[166:169], v154 offset:1024
	ds_read_b128 v[170:173], v154 offset:2048
	ds_read_b128 v[174:177], v154 offset:3072
	v_add_u32_e32 v154, s87, v157
	ds_read_b128 v[178:181], v154
	ds_read_b128 v[182:185], v154 offset:1024
	ds_read_b128 v[186:189], v154 offset:2048
	ds_read_b128 v[190:193], v154 offset:3072
	v_lshl_add_u64 v[154:155], s[40:41], 0, v[148:149]
	s_add_i32 m0, s42, 0xc000
	ds_read_b128 v[196:199], v160
	ds_read_b128 v[200:203], v160 offset:1024
	ds_read_b128 v[204:207], v160 offset:2048
	ds_read_b128 v[208:211], v160 offset:3072
	ds_read_b128 v[212:215], v160 offset:4096
	ds_read_b128 v[216:219], v160 offset:5120
	ds_read_b128 v[228:231], v160 offset:6144
	ds_read_b128 v[232:235], v160 offset:7168
	global_load_lds_dwordx4 v[154:155], off
	v_lshl_add_u64 v[154:155], s[40:41], 0, v[150:151]
	s_add_i32 m0, s42, 0xe000
	s_nop 0
	global_load_lds_dwordx4 v[154:155], off
	s_waitcnt vmcnt(8)
	s_waitcnt lgkmcnt(0)
	s_barrier
	s_setprio 1
	s_waitcnt lgkmcnt(0)
	v_mfma_f32_16x16x32_f16 v[134:137], v[162:165], v[196:199], v[134:137]
	v_mfma_f32_16x16x32_f16 v[130:133], v[170:173], v[196:199], v[130:133]
	v_mfma_f32_16x16x32_f16 v[118:121], v[162:165], v[204:207], v[118:121]
	v_mfma_f32_16x16x32_f16 v[114:117], v[170:173], v[204:207], v[114:117]
	v_mfma_f32_16x16x32_f16 v[102:105], v[162:165], v[212:215], v[102:105]
	v_mfma_f32_16x16x32_f16 v[98:101], v[170:173], v[212:215], v[98:101]
	v_mfma_f32_16x16x32_f16 v[86:89], v[162:165], v[228:231], v[86:89]
	v_mfma_f32_16x16x32_f16 v[82:85], v[170:173], v[228:231], v[82:85]
	v_mfma_f32_16x16x32_f16 v[134:137], v[166:169], v[200:203], v[134:137]
	v_mfma_f32_16x16x32_f16 v[130:133], v[174:177], v[200:203], v[130:133]
	v_mfma_f32_16x16x32_f16 v[118:121], v[166:169], v[208:211], v[118:121]
	v_mfma_f32_16x16x32_f16 v[114:117], v[174:177], v[208:211], v[114:117]
	v_mfma_f32_16x16x32_f16 v[102:105], v[166:169], v[216:219], v[102:105]
	v_mfma_f32_16x16x32_f16 v[98:101], v[174:177], v[216:219], v[98:101]
	v_mfma_f32_16x16x32_f16 v[86:89], v[166:169], v[232:235], v[86:89]
	v_mfma_f32_16x16x32_f16 v[82:85], v[174:177], v[232:235], v[82:85]
	v_mfma_f32_16x16x32_f16 v[126:129], v[178:181], v[196:199], v[126:129]
	v_mfma_f32_16x16x32_f16 v[122:125], v[186:189], v[196:199], v[122:125]
	v_mfma_f32_16x16x32_f16 v[110:113], v[178:181], v[204:207], v[110:113]
	v_mfma_f32_16x16x32_f16 v[106:109], v[186:189], v[204:207], v[106:109]
	v_mfma_f32_16x16x32_f16 v[94:97], v[178:181], v[212:215], v[94:97]
	v_mfma_f32_16x16x32_f16 v[90:93], v[186:189], v[212:215], v[90:93]
	v_mfma_f32_16x16x32_f16 v[78:81], v[178:181], v[228:231], v[78:81]
	v_mfma_f32_16x16x32_f16 v[74:77], v[186:189], v[228:231], v[74:77]
	v_mfma_f32_16x16x32_f16 v[126:129], v[182:185], v[200:203], v[126:129]
	v_mfma_f32_16x16x32_f16 v[122:125], v[190:193], v[200:203], v[122:125]
	v_mfma_f32_16x16x32_f16 v[110:113], v[182:185], v[208:211], v[110:113]
	v_mfma_f32_16x16x32_f16 v[106:109], v[190:193], v[208:211], v[106:109]
	v_mfma_f32_16x16x32_f16 v[94:97], v[182:185], v[216:219], v[94:97]
	v_mfma_f32_16x16x32_f16 v[90:93], v[190:193], v[216:219], v[90:93]
	v_mfma_f32_16x16x32_f16 v[78:81], v[182:185], v[232:235], v[78:81]
	v_mfma_f32_16x16x32_f16 v[74:77], v[190:193], v[232:235], v[74:77]
	s_setprio 0
	s_barrier
	s_add_i32 s84, s84, s29
	v_lshl_add_u64 v[154:155], s[66:67], 0, v[142:143]
	s_mov_b32 m0, s84
	ds_read_b128 v[196:199], v160 offset:16384
	ds_read_b128 v[200:203], v160 offset:17408
	ds_read_b128 v[204:207], v160 offset:18432
	ds_read_b128 v[208:211], v160 offset:19456
	ds_read_b128 v[212:215], v160 offset:20480
	ds_read_b128 v[216:219], v160 offset:21504
	ds_read_b128 v[228:231], v160 offset:22528
	ds_read_b128 v[232:235], v160 offset:23552
	global_load_lds_dwordx4 v[154:155], off
	s_add_i32 m0, s84, 0x2000
	s_add_u32 s84, s66, 0x40000
	v_lshl_add_u64 v[236:237], s[66:67], 0, v[138:139]
	s_addc_u32 s85, s67, 0
	s_add_i32 s87, s87, s29
	global_load_lds_dwordx4 v[236:237], off
	v_lshl_add_u64 v[238:239], s[84:85], 0, v[142:143]
	s_mov_b32 m0, s87
	v_lshl_add_u64 v[240:241], s[72:73], 0, v[140:141]
	global_load_lds_dwordx4 v[238:239], off
	v_lshl_add_u64 v[238:239], s[84:85], 0, v[138:139]
	s_add_i32 m0, s87, 0x2000
	s_nop 0
	global_load_lds_dwordx4 v[238:239], off
	v_lshl_add_u64 v[238:239], s[72:73], 0, v[144:145]
	s_mov_b32 m0, s42
	s_nop 0
	global_load_lds_dwordx4 v[238:239], off
	s_mov_b32 m0, s43
	s_nop 0
	global_load_lds_dwordx4 v[240:241], off
	s_waitcnt vmcnt(8)
	s_waitcnt lgkmcnt(0)
	s_barrier
	s_setprio 1
	s_waitcnt lgkmcnt(0)
	v_mfma_f32_16x16x32_f16 v[70:73], v[162:165], v[196:199], v[70:73]
	v_mfma_f32_16x16x32_f16 v[66:69], v[170:173], v[196:199], v[66:69]
	v_mfma_f32_16x16x32_f16 v[54:57], v[162:165], v[204:207], v[54:57]
	v_mfma_f32_16x16x32_f16 v[50:53], v[170:173], v[204:207], v[50:53]
	v_mfma_f32_16x16x32_f16 v[38:41], v[162:165], v[212:215], v[38:41]
	v_mfma_f32_16x16x32_f16 v[34:37], v[170:173], v[212:215], v[34:37]
	v_mfma_f32_16x16x32_f16 v[22:25], v[162:165], v[228:231], v[22:25]
	v_mfma_f32_16x16x32_f16 v[18:21], v[170:173], v[228:231], v[18:21]
	v_mfma_f32_16x16x32_f16 v[70:73], v[166:169], v[200:203], v[70:73]
	v_mfma_f32_16x16x32_f16 v[66:69], v[174:177], v[200:203], v[66:69]
	v_mfma_f32_16x16x32_f16 v[54:57], v[166:169], v[208:211], v[54:57]
	v_mfma_f32_16x16x32_f16 v[50:53], v[174:177], v[208:211], v[50:53]
	v_mfma_f32_16x16x32_f16 v[38:41], v[166:169], v[216:219], v[38:41]
	v_mfma_f32_16x16x32_f16 v[34:37], v[174:177], v[216:219], v[34:37]
	v_mfma_f32_16x16x32_f16 v[22:25], v[166:169], v[232:235], v[22:25]
	v_mfma_f32_16x16x32_f16 v[18:21], v[174:177], v[232:235], v[18:21]
	v_mfma_f32_16x16x32_f16 v[62:65], v[178:181], v[196:199], v[62:65]
	v_mfma_f32_16x16x32_f16 v[58:61], v[186:189], v[196:199], v[58:61]
	v_mfma_f32_16x16x32_f16 v[46:49], v[178:181], v[204:207], v[46:49]
	v_mfma_f32_16x16x32_f16 v[42:45], v[186:189], v[204:207], v[42:45]
	v_mfma_f32_16x16x32_f16 v[30:33], v[178:181], v[212:215], v[30:33]
	v_mfma_f32_16x16x32_f16 v[26:29], v[186:189], v[212:215], v[26:29]
	v_mfma_f32_16x16x32_f16 v[14:17], v[178:181], v[228:231], v[14:17]
	v_mfma_f32_16x16x32_f16 v[10:13], v[186:189], v[228:231], v[10:13]
	v_mfma_f32_16x16x32_f16 v[62:65], v[182:185], v[200:203], v[62:65]
	v_mfma_f32_16x16x32_f16 v[58:61], v[190:193], v[200:203], v[58:61]
	v_mfma_f32_16x16x32_f16 v[46:49], v[182:185], v[208:211], v[46:49]
	v_mfma_f32_16x16x32_f16 v[42:45], v[190:193], v[208:211], v[42:45]
	v_mfma_f32_16x16x32_f16 v[30:33], v[182:185], v[216:219], v[30:33]
	v_mfma_f32_16x16x32_f16 v[26:29], v[190:193], v[216:219], v[26:29]
	v_mfma_f32_16x16x32_f16 v[14:17], v[182:185], v[232:235], v[14:17]
	v_mfma_f32_16x16x32_f16 v[10:13], v[190:193], v[232:235], v[10:13]
	s_setprio 0
	s_barrier
	s_add_i32 s84, 0, 0x18000
	v_add_u32_e32 v161, s84, v157
	s_add_i32 s85, 0, 0x1c000
	ds_read_b128 v[162:165], v161
	ds_read_b128 v[166:169], v161 offset:1024
	ds_read_b128 v[170:173], v161 offset:2048
	ds_read_b128 v[174:177], v161 offset:3072
	v_add_u32_e32 v161, s85, v157
	ds_read_b128 v[178:181], v161
	ds_read_b128 v[182:185], v161 offset:1024
	ds_read_b128 v[186:189], v161 offset:2048
	ds_read_b128 v[190:193], v161 offset:3072
	s_add_u32 s72, s72, 0x40000
	s_addc_u32 s73, s73, 0
	s_mov_b32 m0, s46
	v_lshl_add_u64 v[242:243], s[72:73], 0, v[144:145]
	ds_read_b128 v[196:199], v160 offset:32768
	ds_read_b128 v[200:203], v160 offset:33792
	ds_read_b128 v[204:207], v160 offset:34816
	ds_read_b128 v[208:211], v160 offset:35840
	ds_read_b128 v[212:215], v160 offset:36864
	ds_read_b128 v[216:219], v160 offset:37888
	ds_read_b128 v[228:231], v160 offset:38912
	ds_read_b128 v[232:235], v160 offset:39936
	global_load_lds_dwordx4 v[242:243], off
	v_lshl_add_u64 v[242:243], s[72:73], 0, v[140:141]
	s_mov_b32 m0, s47
	s_nop 0
	global_load_lds_dwordx4 v[242:243], off
	s_waitcnt vmcnt(8)
	s_waitcnt lgkmcnt(0)
	s_barrier
	s_setprio 1
	s_waitcnt lgkmcnt(0)
	v_mfma_f32_16x16x32_f16 v[134:137], v[162:165], v[196:199], v[134:137]
	v_mfma_f32_16x16x32_f16 v[130:133], v[170:173], v[196:199], v[130:133]
	v_mfma_f32_16x16x32_f16 v[118:121], v[162:165], v[204:207], v[118:121]
	v_mfma_f32_16x16x32_f16 v[114:117], v[170:173], v[204:207], v[114:117]
	v_mfma_f32_16x16x32_f16 v[102:105], v[162:165], v[212:215], v[102:105]
	v_mfma_f32_16x16x32_f16 v[98:101], v[170:173], v[212:215], v[98:101]
	v_mfma_f32_16x16x32_f16 v[86:89], v[162:165], v[228:231], v[86:89]
	v_mfma_f32_16x16x32_f16 v[82:85], v[170:173], v[228:231], v[82:85]
	v_mfma_f32_16x16x32_f16 v[134:137], v[166:169], v[200:203], v[134:137]
	v_mfma_f32_16x16x32_f16 v[130:133], v[174:177], v[200:203], v[130:133]
	v_mfma_f32_16x16x32_f16 v[118:121], v[166:169], v[208:211], v[118:121]
	v_mfma_f32_16x16x32_f16 v[114:117], v[174:177], v[208:211], v[114:117]
	v_mfma_f32_16x16x32_f16 v[102:105], v[166:169], v[216:219], v[102:105]
	v_mfma_f32_16x16x32_f16 v[98:101], v[174:177], v[216:219], v[98:101]
	v_mfma_f32_16x16x32_f16 v[86:89], v[166:169], v[232:235], v[86:89]
	v_mfma_f32_16x16x32_f16 v[82:85], v[174:177], v[232:235], v[82:85]
	v_mfma_f32_16x16x32_f16 v[126:129], v[178:181], v[196:199], v[126:129]
	v_mfma_f32_16x16x32_f16 v[122:125], v[186:189], v[196:199], v[122:125]
	v_mfma_f32_16x16x32_f16 v[110:113], v[178:181], v[204:207], v[110:113]
	v_mfma_f32_16x16x32_f16 v[106:109], v[186:189], v[204:207], v[106:109]
	v_mfma_f32_16x16x32_f16 v[94:97], v[178:181], v[212:215], v[94:97]
	v_mfma_f32_16x16x32_f16 v[90:93], v[186:189], v[212:215], v[90:93]
	v_mfma_f32_16x16x32_f16 v[78:81], v[178:181], v[228:231], v[78:81]
	v_mfma_f32_16x16x32_f16 v[74:77], v[186:189], v[228:231], v[74:77]
	v_mfma_f32_16x16x32_f16 v[126:129], v[182:185], v[200:203], v[126:129]
	v_mfma_f32_16x16x32_f16 v[122:125], v[190:193], v[200:203], v[122:125]
	v_mfma_f32_16x16x32_f16 v[110:113], v[182:185], v[208:211], v[110:113]
	v_mfma_f32_16x16x32_f16 v[106:109], v[190:193], v[208:211], v[106:109]
	v_mfma_f32_16x16x32_f16 v[94:97], v[182:185], v[216:219], v[94:97]
	v_mfma_f32_16x16x32_f16 v[90:93], v[190:193], v[216:219], v[90:93]
	v_mfma_f32_16x16x32_f16 v[78:81], v[182:185], v[232:235], v[78:81]
	v_mfma_f32_16x16x32_f16 v[74:77], v[190:193], v[232:235], v[74:77]
	s_setprio 0
	s_barrier
	s_add_i32 s72, s84, s29
	v_lshl_add_u64 v[154:155], v[154:155], 0, s[34:35]
	s_mov_b32 m0, s72
	ds_read_b128 v[196:199], v160 offset:49152
	ds_read_b128 v[200:203], v160 offset:50176
	ds_read_b128 v[204:207], v160 offset:51200
	ds_read_b128 v[208:211], v160 offset:52224
	ds_read_b128 v[212:215], v160 offset:53248
	ds_read_b128 v[216:219], v160 offset:54272
	ds_read_b128 v[228:231], v160 offset:55296
	ds_read_b128 v[232:235], v160 offset:56320
	global_load_lds_dwordx4 v[154:155], off
	s_add_i32 m0, s72, 0x2000
	s_add_u32 s66, s66, 0x40080
	v_lshl_add_u64 v[154:155], v[236:237], 0, s[34:35]
	s_addc_u32 s67, s67, 0
	s_add_i32 s72, s85, s29
	global_load_lds_dwordx4 v[154:155], off
	v_lshl_add_u64 v[154:155], s[66:67], 0, v[142:143]
	s_mov_b32 m0, s72
	s_nop 0
	global_load_lds_dwordx4 v[154:155], off
	v_lshl_add_u64 v[154:155], s[66:67], 0, v[138:139]
	s_add_i32 m0, s72, 0x2000
	s_nop 0
	global_load_lds_dwordx4 v[154:155], off
	v_lshl_add_u64 v[154:155], v[238:239], 0, s[34:35]
	s_mov_b32 m0, s68
	s_nop 0
	global_load_lds_dwordx4 v[154:155], off
	v_lshl_add_u64 v[154:155], v[240:241], 0, s[34:35]
	s_mov_b32 m0, s69
	s_nop 0
	global_load_lds_dwordx4 v[154:155], off
	s_waitcnt vmcnt(8)
	s_waitcnt lgkmcnt(0)
	s_barrier
	s_setprio 1
	s_waitcnt lgkmcnt(0)
	v_mfma_f32_16x16x32_f16 v[70:73], v[162:165], v[196:199], v[70:73]
	v_mfma_f32_16x16x32_f16 v[66:69], v[170:173], v[196:199], v[66:69]
	v_mfma_f32_16x16x32_f16 v[54:57], v[162:165], v[204:207], v[54:57]
	v_mfma_f32_16x16x32_f16 v[50:53], v[170:173], v[204:207], v[50:53]
	v_mfma_f32_16x16x32_f16 v[38:41], v[162:165], v[212:215], v[38:41]
	v_mfma_f32_16x16x32_f16 v[34:37], v[170:173], v[212:215], v[34:37]
	v_mfma_f32_16x16x32_f16 v[22:25], v[162:165], v[228:231], v[22:25]
	v_mfma_f32_16x16x32_f16 v[18:21], v[170:173], v[228:231], v[18:21]
	v_mfma_f32_16x16x32_f16 v[70:73], v[166:169], v[200:203], v[70:73]
	v_mfma_f32_16x16x32_f16 v[66:69], v[174:177], v[200:203], v[66:69]
	v_mfma_f32_16x16x32_f16 v[54:57], v[166:169], v[208:211], v[54:57]
	v_mfma_f32_16x16x32_f16 v[50:53], v[174:177], v[208:211], v[50:53]
	v_mfma_f32_16x16x32_f16 v[38:41], v[166:169], v[216:219], v[38:41]
	v_mfma_f32_16x16x32_f16 v[34:37], v[174:177], v[216:219], v[34:37]
	v_mfma_f32_16x16x32_f16 v[22:25], v[166:169], v[232:235], v[22:25]
	v_mfma_f32_16x16x32_f16 v[18:21], v[174:177], v[232:235], v[18:21]
	v_mfma_f32_16x16x32_f16 v[62:65], v[178:181], v[196:199], v[62:65]
	v_mfma_f32_16x16x32_f16 v[58:61], v[186:189], v[196:199], v[58:61]
	v_mfma_f32_16x16x32_f16 v[46:49], v[178:181], v[204:207], v[46:49]
	v_mfma_f32_16x16x32_f16 v[42:45], v[186:189], v[204:207], v[42:45]
	v_mfma_f32_16x16x32_f16 v[30:33], v[178:181], v[212:215], v[30:33]
	v_mfma_f32_16x16x32_f16 v[26:29], v[186:189], v[212:215], v[26:29]
	v_mfma_f32_16x16x32_f16 v[14:17], v[178:181], v[228:231], v[14:17]
	v_mfma_f32_16x16x32_f16 v[10:13], v[186:189], v[228:231], v[10:13]
	v_mfma_f32_16x16x32_f16 v[62:65], v[182:185], v[200:203], v[62:65]
	v_mfma_f32_16x16x32_f16 v[58:61], v[190:193], v[200:203], v[58:61]
	v_mfma_f32_16x16x32_f16 v[46:49], v[182:185], v[208:211], v[46:49]
	v_mfma_f32_16x16x32_f16 v[42:45], v[190:193], v[208:211], v[42:45]
	v_mfma_f32_16x16x32_f16 v[30:33], v[182:185], v[216:219], v[30:33]
	v_mfma_f32_16x16x32_f16 v[26:29], v[190:193], v[216:219], v[26:29]
	v_mfma_f32_16x16x32_f16 v[14:17], v[182:185], v[232:235], v[14:17]
	v_mfma_f32_16x16x32_f16 v[10:13], v[190:193], v[232:235], v[10:13]
	s_setprio 0
	s_barrier
	s_add_i32 s83, s83, 2
	s_add_u32 s40, s40, 0x100
	s_addc_u32 s41, s41, 0
	s_add_u32 s81, s81, 0x100
	s_addc_u32 s82, s82, 0
	s_cmp_gt_u32 s83, 13
	s_cbranch_scc0 .LBB0_152
	s_and_b64 vcc, exec, s[48:49]
	s_cbranch_vccz .LBB0_155
	s_barrier

.LBB0_363:
	s_add_i32 s84, s72, 2
	s_add_u32 s85, s40, 0x80
	s_addc_u32 s73, s41, 0
	s_add_i32 s87, 0, 0x10000
	s_cmp_eq_u32 s81, s72
	s_cselect_b32 s73, s56, s73
	s_cselect_b32 s72, s57, s85
	s_cselect_b32 s95, s59, s83
	s_cselect_b32 s94, s61, s82
	s_add_i32 s85, 0, 0x14000
	v_add_u32_e32 v142, s87, v196
	v_add_u32_e32 v170, s85, v196
	ds_read_b128 v[130:133], v142
	ds_read_b128 v[134:137], v142 offset:1024
	ds_read_b128 v[138:141], v142 offset:2048
	ds_read_b128 v[142:145], v142 offset:3072
	ds_read_b128 v[146:149], v170
	ds_read_b128 v[150:153], v170 offset:1024
	ds_read_b128 v[154:157], v170 offset:2048
	ds_read_b128 v[170:173], v170 offset:3072
	v_lshl_add_u64 v[214:215], s[40:41], 0, v[166:167]
	s_add_i32 m0, s46, 0xc000
	ds_read_b128 v[174:177], v200
	ds_read_b128 v[178:181], v200 offset:1024
	ds_read_b128 v[182:185], v200 offset:2048
	ds_read_b128 v[186:189], v200 offset:3072
	ds_read_b128 v[190:193], v200 offset:4096
	ds_read_b128 v[202:205], v200 offset:5120
	ds_read_b128 v[206:209], v200 offset:6144
	ds_read_b128 v[210:213], v200 offset:7168
	global_load_lds_dwordx4 v[214:215], off
	v_lshl_add_u64 v[214:215], s[40:41], 0, v[168:169]
	s_add_i32 m0, s46, 0xe000
	s_nop 0
	global_load_lds_dwordx4 v[214:215], off
	s_waitcnt vmcnt(8)
	s_waitcnt lgkmcnt(0)
	s_barrier
	s_setprio 1
	s_waitcnt lgkmcnt(0)
	v_mfma_f32_16x16x32_bf16 v[126:129], v[130:133], v[174:177], v[126:129]
	v_mfma_f32_16x16x32_bf16 v[122:125], v[138:141], v[174:177], v[122:125]
	v_mfma_f32_16x16x32_bf16 v[110:113], v[130:133], v[182:185], v[110:113]
	v_mfma_f32_16x16x32_bf16 v[106:109], v[138:141], v[182:185], v[106:109]
	v_mfma_f32_16x16x32_bf16 v[94:97], v[130:133], v[190:193], v[94:97]
	v_mfma_f32_16x16x32_bf16 v[90:93], v[138:141], v[190:193], v[90:93]
	v_mfma_f32_16x16x32_bf16 v[78:81], v[130:133], v[206:209], v[78:81]
	v_mfma_f32_16x16x32_bf16 v[74:77], v[138:141], v[206:209], v[74:77]
	v_mfma_f32_16x16x32_bf16 v[126:129], v[134:137], v[178:181], v[126:129]
	v_mfma_f32_16x16x32_bf16 v[122:125], v[142:145], v[178:181], v[122:125]
	v_mfma_f32_16x16x32_bf16 v[110:113], v[134:137], v[186:189], v[110:113]
	v_mfma_f32_16x16x32_bf16 v[106:109], v[142:145], v[186:189], v[106:109]
	v_mfma_f32_16x16x32_bf16 v[94:97], v[134:137], v[202:205], v[94:97]
	v_mfma_f32_16x16x32_bf16 v[90:93], v[142:145], v[202:205], v[90:93]
	v_mfma_f32_16x16x32_bf16 v[78:81], v[134:137], v[210:213], v[78:81]
	v_mfma_f32_16x16x32_bf16 v[74:77], v[142:145], v[210:213], v[74:77]
	v_mfma_f32_16x16x32_bf16 v[118:121], v[146:149], v[174:177], v[118:121]
	v_mfma_f32_16x16x32_bf16 v[114:117], v[154:157], v[174:177], v[114:117]
	v_mfma_f32_16x16x32_bf16 v[102:105], v[146:149], v[182:185], v[102:105]
	v_mfma_f32_16x16x32_bf16 v[98:101], v[154:157], v[182:185], v[98:101]
	v_mfma_f32_16x16x32_bf16 v[86:89], v[146:149], v[190:193], v[86:89]
	v_mfma_f32_16x16x32_bf16 v[82:85], v[154:157], v[190:193], v[82:85]
	v_mfma_f32_16x16x32_bf16 v[70:73], v[146:149], v[206:209], v[70:73]
	v_mfma_f32_16x16x32_bf16 v[66:69], v[154:157], v[206:209], v[66:69]
	v_mfma_f32_16x16x32_bf16 v[118:121], v[150:153], v[178:181], v[118:121]
	v_mfma_f32_16x16x32_bf16 v[114:117], v[170:173], v[178:181], v[114:117]
	v_mfma_f32_16x16x32_bf16 v[102:105], v[150:153], v[186:189], v[102:105]
	v_mfma_f32_16x16x32_bf16 v[98:101], v[170:173], v[186:189], v[98:101]
	v_mfma_f32_16x16x32_bf16 v[86:89], v[150:153], v[202:205], v[86:89]
	v_mfma_f32_16x16x32_bf16 v[82:85], v[170:173], v[202:205], v[82:85]
	v_mfma_f32_16x16x32_bf16 v[70:73], v[150:153], v[210:213], v[70:73]
	v_mfma_f32_16x16x32_bf16 v[66:69], v[170:173], v[210:213], v[66:69]
	s_setprio 0
	s_barrier
	s_add_i32 s87, s87, s42
	v_lshl_add_u64 v[214:215], s[94:95], 0, v[162:163]
	s_mov_b32 m0, s87
	ds_read_b128 v[174:177], v200 offset:16384
	ds_read_b128 v[178:181], v200 offset:17408
	ds_read_b128 v[182:185], v200 offset:18432
	ds_read_b128 v[186:189], v200 offset:19456
	ds_read_b128 v[190:193], v200 offset:20480
	ds_read_b128 v[202:205], v200 offset:21504
	ds_read_b128 v[206:209], v200 offset:22528
	ds_read_b128 v[210:213], v200 offset:23552
	global_load_lds_dwordx4 v[214:215], off
	s_add_i32 m0, s87, 0x2000
	v_lshl_add_u64 v[216:217], s[94:95], 0, v[158:159]
	s_add_u32 s94, s94, s26
	s_addc_u32 s95, s95, 0
	s_add_i32 s85, s85, s42
	global_load_lds_dwordx4 v[216:217], off
	v_lshl_add_u64 v[218:219], s[94:95], 0, v[162:163]
	s_mov_b32 m0, s85
	v_lshl_add_u64 v[228:229], s[94:95], 0, v[158:159]
	global_load_lds_dwordx4 v[218:219], off
	s_add_i32 m0, s85, 0x2000
	v_lshl_add_u64 v[230:231], s[72:73], 0, v[164:165]
	global_load_lds_dwordx4 v[228:229], off
	s_mov_b32 m0, s46
	v_lshl_add_u64 v[232:233], s[72:73], 0, v[160:161]
	global_load_lds_dwordx4 v[230:231], off
	s_mov_b32 m0, s47
	s_nop 0
	global_load_lds_dwordx4 v[232:233], off
	s_waitcnt vmcnt(8)
	s_waitcnt lgkmcnt(0)
	s_barrier
	s_setprio 1
	s_waitcnt lgkmcnt(0)
	v_mfma_f32_16x16x32_bf16 v[62:65], v[130:133], v[174:177], v[62:65]
	v_mfma_f32_16x16x32_bf16 v[58:61], v[138:141], v[174:177], v[58:61]
	v_mfma_f32_16x16x32_bf16 v[46:49], v[130:133], v[182:185], v[46:49]
	v_mfma_f32_16x16x32_bf16 v[42:45], v[138:141], v[182:185], v[42:45]
	v_mfma_f32_16x16x32_bf16 v[30:33], v[130:133], v[190:193], v[30:33]
	v_mfma_f32_16x16x32_bf16 v[26:29], v[138:141], v[190:193], v[26:29]
	v_mfma_f32_16x16x32_bf16 v[14:17], v[130:133], v[206:209], v[14:17]
	v_mfma_f32_16x16x32_bf16 v[10:13], v[138:141], v[206:209], v[10:13]
	v_mfma_f32_16x16x32_bf16 v[62:65], v[134:137], v[178:181], v[62:65]
	v_mfma_f32_16x16x32_bf16 v[58:61], v[142:145], v[178:181], v[58:61]
	v_mfma_f32_16x16x32_bf16 v[46:49], v[134:137], v[186:189], v[46:49]
	v_mfma_f32_16x16x32_bf16 v[42:45], v[142:145], v[186:189], v[42:45]
	v_mfma_f32_16x16x32_bf16 v[30:33], v[134:137], v[202:205], v[30:33]
	v_mfma_f32_16x16x32_bf16 v[26:29], v[142:145], v[202:205], v[26:29]
	v_mfma_f32_16x16x32_bf16 v[14:17], v[134:137], v[210:213], v[14:17]
	v_mfma_f32_16x16x32_bf16 v[10:13], v[142:145], v[210:213], v[10:13]
	v_mfma_f32_16x16x32_bf16 v[54:57], v[146:149], v[174:177], v[54:57]
	v_mfma_f32_16x16x32_bf16 v[50:53], v[154:157], v[174:177], v[50:53]
	v_mfma_f32_16x16x32_bf16 v[38:41], v[146:149], v[182:185], v[38:41]
	v_mfma_f32_16x16x32_bf16 v[34:37], v[154:157], v[182:185], v[34:37]
	v_mfma_f32_16x16x32_bf16 v[22:25], v[146:149], v[190:193], v[22:25]
	v_mfma_f32_16x16x32_bf16 v[18:21], v[154:157], v[190:193], v[18:21]
	v_mfma_f32_16x16x32_bf16 v[6:9], v[146:149], v[206:209], v[6:9]
	v_mfma_f32_16x16x32_bf16 v[2:5], v[154:157], v[206:209], v[2:5]
	v_mfma_f32_16x16x32_bf16 v[54:57], v[150:153], v[178:181], v[54:57]
	v_mfma_f32_16x16x32_bf16 v[50:53], v[170:173], v[178:181], v[50:53]
	v_mfma_f32_16x16x32_bf16 v[38:41], v[150:153], v[186:189], v[38:41]
	v_mfma_f32_16x16x32_bf16 v[34:37], v[170:173], v[186:189], v[34:37]
	v_mfma_f32_16x16x32_bf16 v[22:25], v[150:153], v[202:205], v[22:25]
	v_mfma_f32_16x16x32_bf16 v[18:21], v[170:173], v[202:205], v[18:21]
	v_mfma_f32_16x16x32_bf16 v[6:9], v[150:153], v[210:213], v[6:9]
	v_mfma_f32_16x16x32_bf16 v[2:5], v[170:173], v[210:213], v[2:5]
	s_setprio 0
	s_barrier
	s_add_i32 s85, 0, 0x18000
	s_add_i32 s87, 0, 0x1c000
	v_add_u32_e32 v142, s85, v196
	v_add_u32_e32 v170, s87, v196
	ds_read_b128 v[130:133], v142
	ds_read_b128 v[134:137], v142 offset:1024
	ds_read_b128 v[138:141], v142 offset:2048
	ds_read_b128 v[142:145], v142 offset:3072
	ds_read_b128 v[146:149], v170
	ds_read_b128 v[150:153], v170 offset:1024
	ds_read_b128 v[154:157], v170 offset:2048
	ds_read_b128 v[170:173], v170 offset:3072
	s_add_u32 s72, s72, s26
	s_addc_u32 s73, s73, 0
	s_mov_b32 m0, s68
	v_lshl_add_u64 v[234:235], s[72:73], 0, v[164:165]
	ds_read_b128 v[174:177], v200 offset:32768
	ds_read_b128 v[178:181], v200 offset:33792
	ds_read_b128 v[182:185], v200 offset:34816
	ds_read_b128 v[186:189], v200 offset:35840
	ds_read_b128 v[190:193], v200 offset:36864
	ds_read_b128 v[202:205], v200 offset:37888
	ds_read_b128 v[206:209], v200 offset:38912
	ds_read_b128 v[210:213], v200 offset:39936
	global_load_lds_dwordx4 v[234:235], off
	v_lshl_add_u64 v[234:235], s[72:73], 0, v[160:161]
	s_mov_b32 m0, s69
	s_nop 0
	global_load_lds_dwordx4 v[234:235], off
	s_waitcnt vmcnt(8)
	s_waitcnt lgkmcnt(0)
	s_barrier
	s_setprio 1
	s_waitcnt lgkmcnt(0)
	v_mfma_f32_16x16x32_bf16 v[126:129], v[130:133], v[174:177], v[126:129]
	v_mfma_f32_16x16x32_bf16 v[122:125], v[138:141], v[174:177], v[122:125]
	v_mfma_f32_16x16x32_bf16 v[110:113], v[130:133], v[182:185], v[110:113]
	v_mfma_f32_16x16x32_bf16 v[106:109], v[138:141], v[182:185], v[106:109]
	v_mfma_f32_16x16x32_bf16 v[94:97], v[130:133], v[190:193], v[94:97]
	v_mfma_f32_16x16x32_bf16 v[90:93], v[138:141], v[190:193], v[90:93]
	v_mfma_f32_16x16x32_bf16 v[78:81], v[130:133], v[206:209], v[78:81]
	v_mfma_f32_16x16x32_bf16 v[74:77], v[138:141], v[206:209], v[74:77]
	v_mfma_f32_16x16x32_bf16 v[126:129], v[134:137], v[178:181], v[126:129]
	v_mfma_f32_16x16x32_bf16 v[122:125], v[142:145], v[178:181], v[122:125]
	v_mfma_f32_16x16x32_bf16 v[110:113], v[134:137], v[186:189], v[110:113]
	v_mfma_f32_16x16x32_bf16 v[106:109], v[142:145], v[186:189], v[106:109]
	v_mfma_f32_16x16x32_bf16 v[94:97], v[134:137], v[202:205], v[94:97]
	v_mfma_f32_16x16x32_bf16 v[90:93], v[142:145], v[202:205], v[90:93]
	v_mfma_f32_16x16x32_bf16 v[78:81], v[134:137], v[210:213], v[78:81]
	v_mfma_f32_16x16x32_bf16 v[74:77], v[142:145], v[210:213], v[74:77]
	v_mfma_f32_16x16x32_bf16 v[118:121], v[146:149], v[174:177], v[118:121]
	v_mfma_f32_16x16x32_bf16 v[114:117], v[154:157], v[174:177], v[114:117]
	v_mfma_f32_16x16x32_bf16 v[102:105], v[146:149], v[182:185], v[102:105]
	v_mfma_f32_16x16x32_bf16 v[98:101], v[154:157], v[182:185], v[98:101]
	v_mfma_f32_16x16x32_bf16 v[86:89], v[146:149], v[190:193], v[86:89]
	v_mfma_f32_16x16x32_bf16 v[82:85], v[154:157], v[190:193], v[82:85]
	v_mfma_f32_16x16x32_bf16 v[70:73], v[146:149], v[206:209], v[70:73]
	v_mfma_f32_16x16x32_bf16 v[66:69], v[154:157], v[206:209], v[66:69]
	v_mfma_f32_16x16x32_bf16 v[118:121], v[150:153], v[178:181], v[118:121]
	v_mfma_f32_16x16x32_bf16 v[114:117], v[170:173], v[178:181], v[114:117]
	v_mfma_f32_16x16x32_bf16 v[102:105], v[150:153], v[186:189], v[102:105]
	v_mfma_f32_16x16x32_bf16 v[98:101], v[170:173], v[186:189], v[98:101]
	v_mfma_f32_16x16x32_bf16 v[86:89], v[150:153], v[202:205], v[86:89]
	v_mfma_f32_16x16x32_bf16 v[82:85], v[170:173], v[202:205], v[82:85]
	v_mfma_f32_16x16x32_bf16 v[70:73], v[150:153], v[210:213], v[70:73]
	v_mfma_f32_16x16x32_bf16 v[66:69], v[170:173], v[210:213], v[66:69]
	s_setprio 0
	s_barrier
	s_add_i32 s72, s85, s42
	v_lshl_add_u64 v[214:215], v[214:215], 0, s[34:35]
	s_mov_b32 m0, s72
	ds_read_b128 v[174:177], v200 offset:49152
	ds_read_b128 v[178:181], v200 offset:50176
	ds_read_b128 v[182:185], v200 offset:51200
	ds_read_b128 v[186:189], v200 offset:52224
	ds_read_b128 v[190:193], v200 offset:53248
	ds_read_b128 v[202:205], v200 offset:54272
	ds_read_b128 v[206:209], v200 offset:55296
	ds_read_b128 v[210:213], v200 offset:56320
	global_load_lds_dwordx4 v[214:215], off
	v_lshl_add_u64 v[214:215], v[216:217], 0, s[34:35]
	s_add_i32 m0, s72, 0x2000
	s_add_i32 s72, s87, s42
	global_load_lds_dwordx4 v[214:215], off
	v_lshl_add_u64 v[214:215], v[218:219], 0, s[34:35]
	s_mov_b32 m0, s72
	s_nop 0
	global_load_lds_dwordx4 v[214:215], off
	v_lshl_add_u64 v[214:215], v[228:229], 0, s[34:35]
	s_add_i32 m0, s72, 0x2000
	s_nop 0
	global_load_lds_dwordx4 v[214:215], off
	v_lshl_add_u64 v[214:215], v[230:231], 0, s[34:35]
	s_mov_b32 m0, s79
	s_nop 0
	global_load_lds_dwordx4 v[214:215], off
	v_lshl_add_u64 v[214:215], v[232:233], 0, s[34:35]
	s_mov_b32 m0, s80
	s_nop 0
	global_load_lds_dwordx4 v[214:215], off
	s_waitcnt vmcnt(8)
	s_waitcnt lgkmcnt(0)
	s_barrier
	s_setprio 1
	s_waitcnt lgkmcnt(0)
	v_mfma_f32_16x16x32_bf16 v[62:65], v[130:133], v[174:177], v[62:65]
	v_mfma_f32_16x16x32_bf16 v[58:61], v[138:141], v[174:177], v[58:61]
	v_mfma_f32_16x16x32_bf16 v[46:49], v[130:133], v[182:185], v[46:49]
	v_mfma_f32_16x16x32_bf16 v[42:45], v[138:141], v[182:185], v[42:45]
	v_mfma_f32_16x16x32_bf16 v[30:33], v[130:133], v[190:193], v[30:33]
	v_mfma_f32_16x16x32_bf16 v[26:29], v[138:141], v[190:193], v[26:29]
	v_mfma_f32_16x16x32_bf16 v[14:17], v[130:133], v[206:209], v[14:17]
	v_mfma_f32_16x16x32_bf16 v[10:13], v[138:141], v[206:209], v[10:13]
	v_mfma_f32_16x16x32_bf16 v[62:65], v[134:137], v[178:181], v[62:65]
	v_mfma_f32_16x16x32_bf16 v[58:61], v[142:145], v[178:181], v[58:61]
	v_mfma_f32_16x16x32_bf16 v[46:49], v[134:137], v[186:189], v[46:49]
	v_mfma_f32_16x16x32_bf16 v[42:45], v[142:145], v[186:189], v[42:45]
	v_mfma_f32_16x16x32_bf16 v[30:33], v[134:137], v[202:205], v[30:33]
	v_mfma_f32_16x16x32_bf16 v[26:29], v[142:145], v[202:205], v[26:29]
	v_mfma_f32_16x16x32_bf16 v[14:17], v[134:137], v[210:213], v[14:17]
	v_mfma_f32_16x16x32_bf16 v[10:13], v[142:145], v[210:213], v[10:13]
	v_mfma_f32_16x16x32_bf16 v[54:57], v[146:149], v[174:177], v[54:57]
	v_mfma_f32_16x16x32_bf16 v[50:53], v[154:157], v[174:177], v[50:53]
	v_mfma_f32_16x16x32_bf16 v[38:41], v[146:149], v[182:185], v[38:41]
	v_mfma_f32_16x16x32_bf16 v[34:37], v[154:157], v[182:185], v[34:37]
	v_mfma_f32_16x16x32_bf16 v[22:25], v[146:149], v[190:193], v[22:25]
	v_mfma_f32_16x16x32_bf16 v[18:21], v[154:157], v[190:193], v[18:21]
	v_mfma_f32_16x16x32_bf16 v[6:9], v[146:149], v[206:209], v[6:9]
	v_mfma_f32_16x16x32_bf16 v[2:5], v[154:157], v[206:209], v[2:5]
	v_mfma_f32_16x16x32_bf16 v[54:57], v[150:153], v[178:181], v[54:57]
	v_mfma_f32_16x16x32_bf16 v[50:53], v[170:173], v[178:181], v[50:53]
	v_mfma_f32_16x16x32_bf16 v[38:41], v[150:153], v[186:189], v[38:41]
	v_mfma_f32_16x16x32_bf16 v[34:37], v[170:173], v[186:189], v[34:37]
	v_mfma_f32_16x16x32_bf16 v[22:25], v[150:153], v[202:205], v[22:25]
	v_mfma_f32_16x16x32_bf16 v[18:21], v[170:173], v[202:205], v[18:21]
	v_mfma_f32_16x16x32_bf16 v[6:9], v[150:153], v[210:213], v[6:9]
	v_mfma_f32_16x16x32_bf16 v[2:5], v[170:173], v[210:213], v[2:5]
	s_setprio 0
	s_barrier
	s_add_u32 s40, s40, 0x100
	s_addc_u32 s41, s41, 0
	s_add_u32 s82, s82, 0x100
	s_addc_u32 s83, s83, 0
	s_cmp_ge_u32 s84, s78
	s_mov_b32 s72, s84
	s_cbranch_scc0 .LBB0_363
	v_lshl_add_u32 v172, s27, 8, v197
	v_lshl_add_u32 v174, s50, 8, v1
	v_ashrrev_i32_e32 v173, 31, v172
	v_ashrrev_i32_e32 v175, 31, v174
	v_lshl_add_u64 v[170:171], v[172:173], 1, s[30:31]
	v_lshlrev_b64 v[130:131], 11, v[174:175]
	v_or_b32_e32 v184, 16, v174
	v_lshl_add_u64 v[188:189], v[170:171], 0, v[130:131]
	v_ashrrev_i32_e32 v185, 31, v184
	v_or_b32_e32 v180, 32, v174
	global_load_dwordx4 v[202:205], v[188:189], off
	global_load_dwordx4 v[154:157], v[188:189], off offset:256
	v_lshlrev_b64 v[130:131], 11, v[184:185]
	v_ashrrev_i32_e32 v181, 31, v180
	v_or_b32_e32 v176, 48, v174
	v_lshl_add_u64 v[186:187], v[170:171], 0, v[130:131]
	v_lshlrev_b64 v[130:131], 11, v[180:181]
	v_ashrrev_i32_e32 v177, 31, v176
	v_lshl_add_u64 v[182:183], v[170:171], 0, v[130:131]
	v_lshlrev_b64 v[130:131], 11, v[176:177]
	v_lshl_add_u64 v[178:179], v[170:171], 0, v[130:131]
	global_load_dwordx4 v[150:153], v[186:187], off
	global_load_dwordx4 v[146:149], v[186:187], off offset:256
	global_load_dwordx4 v[142:145], v[182:183], off
	global_load_dwordx4 v[138:141], v[182:183], off offset:256
	global_load_dwordx4 v[134:137], v[178:179], off
	global_load_dwordx4 v[130:133], v[178:179], off offset:256
	v_cndmask_b32_e64 v190, 0, 1, s[54:55]
	v_lshlrev_b64 v[192:193], 10, v[174:175]
	v_cmp_ne_u32_e64 s[40:41], 1, v190
	v_lshl_add_u64 v[190:191], v[192:193], 0, v[172:173]
	s_andn2_b64 vcc, exec, s[54:55]
	v_lshl_add_u64 v[190:191], v[190:191], 2, s[24:25]
	s_waitcnt vmcnt(0)
	v_cvt_f32_f16_e32 v206, v202
	v_cvt_f32_f16_sdwa v207, v202 dst_sel:DWORD dst_unused:UNUSED_PAD src0_sel:WORD_1
	v_cvt_f32_f16_e32 v202, v203
	v_cvt_f32_f16_sdwa v203, v203 dst_sel:DWORD dst_unused:UNUSED_PAD src0_sel:WORD_1
	v_cvt_f32_f16_e32 v208, v204
	v_cvt_f32_f16_e32 v210, v205
	v_cvt_f32_f16_sdwa v211, v205 dst_sel:DWORD dst_unused:UNUSED_PAD src0_sel:WORD_1
	v_cvt_f32_f16_sdwa v209, v204 dst_sel:DWORD dst_unused:UNUSED_PAD src0_sel:WORD_1
	v_pk_add_f32 v[128:129], v[128:129], v[202:203]
	v_pk_add_f32 v[126:127], v[126:127], v[206:207]
	v_pk_add_f32 v[124:125], v[124:125], v[210:211]
	v_pk_add_f32 v[122:123], v[122:123], v[208:209]
	s_cbranch_vccnz .LBB0_428
	global_store_dwordx4 v[190:191], v[126:129], off
	global_store_dwordx4 v[190:191], v[122:125], off offset:16
	s_cbranch_execnz .LBB0_367

.LBB0_664:
	s_add_u32 s42, s38, 0xfffc0080
	s_addc_u32 s43, s39, -1
	s_add_i32 s94, 0, 0x10000
	s_cmp_eq_u32 s91, 12
	s_cselect_b32 s73, s84, s43
	s_cselect_b32 s72, s85, s42
	s_cselect_b32 s43, s59, s79
	s_cselect_b32 s42, s87, s78
	s_add_i32 s96, 0, 0x14000
	v_add_u32_e32 v166, s94, v175
	v_add_u32_e32 v192, s96, v175
	ds_read_b128 v[154:157], v166
	ds_read_b128 v[158:161], v166 offset:1024
	ds_read_b128 v[162:165], v166 offset:2048
	ds_read_b128 v[166:169], v166 offset:3072
	ds_read_b128 v[170:173], v192
	ds_read_b128 v[188:191], v192 offset:1024
	ds_read_b128 v[196:199], v192 offset:2048
	ds_read_b128 v[200:203], v192 offset:3072
	v_lshl_add_u64 v[192:193], s[38:39], 0, v[150:151]
	s_add_i32 m0, s46, 0xc000
	ds_read_b128 v[204:207], v187
	ds_read_b128 v[208:211], v187 offset:1024
	ds_read_b128 v[212:215], v187 offset:2048
	ds_read_b128 v[216:219], v187 offset:3072
	ds_read_b128 v[228:231], v187 offset:4096
	ds_read_b128 v[232:235], v187 offset:5120
	ds_read_b128 v[236:239], v187 offset:6144
	ds_read_b128 v[240:243], v187 offset:7168
	global_load_lds_dwordx4 v[192:193], off
	v_lshl_add_u64 v[192:193], s[38:39], 0, v[152:153]
	s_add_i32 m0, s46, 0xe000
	s_nop 0
	global_load_lds_dwordx4 v[192:193], off
	s_waitcnt vmcnt(8)
	s_waitcnt lgkmcnt(0)
	s_barrier
	s_setprio 1
	s_waitcnt lgkmcnt(0)
	v_mfma_f32_16x16x32_f16 v[134:137], v[154:157], v[204:207], v[134:137]
	v_mfma_f32_16x16x32_f16 v[130:133], v[162:165], v[204:207], v[130:133]
	v_mfma_f32_16x16x32_f16 v[118:121], v[154:157], v[212:215], v[118:121]
	v_mfma_f32_16x16x32_f16 v[114:117], v[162:165], v[212:215], v[114:117]
	v_mfma_f32_16x16x32_f16 v[102:105], v[154:157], v[228:231], v[102:105]
	v_mfma_f32_16x16x32_f16 v[98:101], v[162:165], v[228:231], v[98:101]
	v_mfma_f32_16x16x32_f16 v[86:89], v[154:157], v[236:239], v[86:89]
	v_mfma_f32_16x16x32_f16 v[82:85], v[162:165], v[236:239], v[82:85]
	v_mfma_f32_16x16x32_f16 v[134:137], v[158:161], v[208:211], v[134:137]
	v_mfma_f32_16x16x32_f16 v[130:133], v[166:169], v[208:211], v[130:133]
	v_mfma_f32_16x16x32_f16 v[118:121], v[158:161], v[216:219], v[118:121]
	v_mfma_f32_16x16x32_f16 v[114:117], v[166:169], v[216:219], v[114:117]
	v_mfma_f32_16x16x32_f16 v[102:105], v[158:161], v[232:235], v[102:105]
	v_mfma_f32_16x16x32_f16 v[98:101], v[166:169], v[232:235], v[98:101]
	v_mfma_f32_16x16x32_f16 v[86:89], v[158:161], v[240:243], v[86:89]
	v_mfma_f32_16x16x32_f16 v[82:85], v[166:169], v[240:243], v[82:85]
	v_mfma_f32_16x16x32_f16 v[126:129], v[170:173], v[204:207], v[126:129]
	v_mfma_f32_16x16x32_f16 v[122:125], v[196:199], v[204:207], v[122:125]
	v_mfma_f32_16x16x32_f16 v[110:113], v[170:173], v[212:215], v[110:113]
	v_mfma_f32_16x16x32_f16 v[106:109], v[196:199], v[212:215], v[106:109]
	v_mfma_f32_16x16x32_f16 v[94:97], v[170:173], v[228:231], v[94:97]
	v_mfma_f32_16x16x32_f16 v[90:93], v[196:199], v[228:231], v[90:93]
	v_mfma_f32_16x16x32_f16 v[78:81], v[170:173], v[236:239], v[78:81]
	v_mfma_f32_16x16x32_f16 v[74:77], v[196:199], v[236:239], v[74:77]
	v_mfma_f32_16x16x32_f16 v[126:129], v[188:191], v[208:211], v[126:129]
	v_mfma_f32_16x16x32_f16 v[122:125], v[200:203], v[208:211], v[122:125]
	v_mfma_f32_16x16x32_f16 v[110:113], v[188:191], v[216:219], v[110:113]
	v_mfma_f32_16x16x32_f16 v[106:109], v[200:203], v[216:219], v[106:109]
	v_mfma_f32_16x16x32_f16 v[94:97], v[188:191], v[232:235], v[94:97]
	v_mfma_f32_16x16x32_f16 v[90:93], v[200:203], v[232:235], v[90:93]
	v_mfma_f32_16x16x32_f16 v[78:81], v[188:191], v[240:243], v[78:81]
	v_mfma_f32_16x16x32_f16 v[74:77], v[200:203], v[240:243], v[74:77]
	s_setprio 0
	s_barrier
	s_add_i32 s94, s94, s29
	v_lshl_add_u64 v[192:193], s[42:43], 0, v[142:143]
	s_mov_b32 m0, s94
	ds_read_b128 v[204:207], v187 offset:16384
	ds_read_b128 v[208:211], v187 offset:17408
	ds_read_b128 v[212:215], v187 offset:18432
	ds_read_b128 v[216:219], v187 offset:19456
	ds_read_b128 v[228:231], v187 offset:20480
	ds_read_b128 v[232:235], v187 offset:21504
	ds_read_b128 v[236:239], v187 offset:22528
	ds_read_b128 v[240:243], v187 offset:23552
	global_load_lds_dwordx4 v[192:193], off
	s_add_i32 m0, s94, 0x2000
	s_add_u32 s94, s42, 0x40000
	v_lshl_add_u64 v[244:245], s[42:43], 0, v[138:139]
	s_addc_u32 s95, s43, 0
	s_add_i32 s96, s96, s29
	global_load_lds_dwordx4 v[244:245], off
	v_lshl_add_u64 v[246:247], s[94:95], 0, v[142:143]
	s_mov_b32 m0, s96
	v_lshl_add_u64 v[248:249], s[72:73], 0, v[140:141]
	global_load_lds_dwordx4 v[246:247], off
	v_lshl_add_u64 v[246:247], s[94:95], 0, v[138:139]
	s_add_i32 m0, s96, 0x2000
	s_nop 0
	global_load_lds_dwordx4 v[246:247], off
	v_lshl_add_u64 v[246:247], s[72:73], 0, v[144:145]
	s_mov_b32 m0, s46
	s_nop 0
	global_load_lds_dwordx4 v[246:247], off
	s_mov_b32 m0, s47
	s_nop 0
	global_load_lds_dwordx4 v[248:249], off
	s_waitcnt vmcnt(8)
	s_waitcnt lgkmcnt(0)
	s_barrier
	s_setprio 1
	s_waitcnt lgkmcnt(0)
	v_mfma_f32_16x16x32_f16 v[70:73], v[154:157], v[204:207], v[70:73]
	v_mfma_f32_16x16x32_f16 v[66:69], v[162:165], v[204:207], v[66:69]
	v_mfma_f32_16x16x32_f16 v[54:57], v[154:157], v[212:215], v[54:57]
	v_mfma_f32_16x16x32_f16 v[50:53], v[162:165], v[212:215], v[50:53]
	v_mfma_f32_16x16x32_f16 v[38:41], v[154:157], v[228:231], v[38:41]
	v_mfma_f32_16x16x32_f16 v[34:37], v[162:165], v[228:231], v[34:37]
	v_mfma_f32_16x16x32_f16 v[22:25], v[154:157], v[236:239], v[22:25]
	v_mfma_f32_16x16x32_f16 v[18:21], v[162:165], v[236:239], v[18:21]
	v_mfma_f32_16x16x32_f16 v[70:73], v[158:161], v[208:211], v[70:73]
	v_mfma_f32_16x16x32_f16 v[66:69], v[166:169], v[208:211], v[66:69]
	v_mfma_f32_16x16x32_f16 v[54:57], v[158:161], v[216:219], v[54:57]
	v_mfma_f32_16x16x32_f16 v[50:53], v[166:169], v[216:219], v[50:53]
	v_mfma_f32_16x16x32_f16 v[38:41], v[158:161], v[232:235], v[38:41]
	v_mfma_f32_16x16x32_f16 v[34:37], v[166:169], v[232:235], v[34:37]
	v_mfma_f32_16x16x32_f16 v[22:25], v[158:161], v[240:243], v[22:25]
	v_mfma_f32_16x16x32_f16 v[18:21], v[166:169], v[240:243], v[18:21]
	v_mfma_f32_16x16x32_f16 v[62:65], v[170:173], v[204:207], v[62:65]
	v_mfma_f32_16x16x32_f16 v[58:61], v[196:199], v[204:207], v[58:61]
	v_mfma_f32_16x16x32_f16 v[46:49], v[170:173], v[212:215], v[46:49]
	v_mfma_f32_16x16x32_f16 v[42:45], v[196:199], v[212:215], v[42:45]
	v_mfma_f32_16x16x32_f16 v[30:33], v[170:173], v[228:231], v[30:33]
	v_mfma_f32_16x16x32_f16 v[26:29], v[196:199], v[228:231], v[26:29]
	v_mfma_f32_16x16x32_f16 v[14:17], v[170:173], v[236:239], v[14:17]
	v_mfma_f32_16x16x32_f16 v[10:13], v[196:199], v[236:239], v[10:13]
	v_mfma_f32_16x16x32_f16 v[62:65], v[188:191], v[208:211], v[62:65]
	v_mfma_f32_16x16x32_f16 v[58:61], v[200:203], v[208:211], v[58:61]
	v_mfma_f32_16x16x32_f16 v[46:49], v[188:191], v[216:219], v[46:49]
	v_mfma_f32_16x16x32_f16 v[42:45], v[200:203], v[216:219], v[42:45]
	v_mfma_f32_16x16x32_f16 v[30:33], v[188:191], v[232:235], v[30:33]
	v_mfma_f32_16x16x32_f16 v[26:29], v[200:203], v[232:235], v[26:29]
	v_mfma_f32_16x16x32_f16 v[14:17], v[188:191], v[240:243], v[14:17]
	v_mfma_f32_16x16x32_f16 v[10:13], v[200:203], v[240:243], v[10:13]
	s_setprio 0
	s_barrier
	s_add_i32 s94, 0, 0x18000
	s_add_i32 s95, 0, 0x1c000
	v_add_u32_e32 v166, s94, v175
	v_add_u32_e32 v200, s95, v175
	ds_read_b128 v[154:157], v166
	ds_read_b128 v[158:161], v166 offset:1024
	ds_read_b128 v[162:165], v166 offset:2048
	ds_read_b128 v[166:169], v166 offset:3072
	ds_read_b128 v[170:173], v200
	ds_read_b128 v[188:191], v200 offset:1024
	ds_read_b128 v[196:199], v200 offset:2048
	ds_read_b128 v[200:203], v200 offset:3072
	s_add_u32 s72, s72, 0x40000
	s_addc_u32 s73, s73, 0
	s_mov_b32 m0, s56
	v_lshl_add_u64 v[250:251], s[72:73], 0, v[144:145]
	ds_read_b128 v[204:207], v187 offset:32768
	ds_read_b128 v[208:211], v187 offset:33792
	ds_read_b128 v[212:215], v187 offset:34816
	ds_read_b128 v[216:219], v187 offset:35840
	ds_read_b128 v[228:231], v187 offset:36864
	ds_read_b128 v[232:235], v187 offset:37888
	ds_read_b128 v[236:239], v187 offset:38912
	ds_read_b128 v[240:243], v187 offset:39936
	global_load_lds_dwordx4 v[250:251], off
	v_lshl_add_u64 v[250:251], s[72:73], 0, v[140:141]
	s_mov_b32 m0, s57
	s_nop 0
	global_load_lds_dwordx4 v[250:251], off
	s_waitcnt vmcnt(8)
	s_waitcnt lgkmcnt(0)
	s_barrier
	s_setprio 1
	s_waitcnt lgkmcnt(0)
	v_mfma_f32_16x16x32_f16 v[134:137], v[154:157], v[204:207], v[134:137]
	v_mfma_f32_16x16x32_f16 v[130:133], v[162:165], v[204:207], v[130:133]
	v_mfma_f32_16x16x32_f16 v[118:121], v[154:157], v[212:215], v[118:121]
	v_mfma_f32_16x16x32_f16 v[114:117], v[162:165], v[212:215], v[114:117]
	v_mfma_f32_16x16x32_f16 v[102:105], v[154:157], v[228:231], v[102:105]
	v_mfma_f32_16x16x32_f16 v[98:101], v[162:165], v[228:231], v[98:101]
	v_mfma_f32_16x16x32_f16 v[86:89], v[154:157], v[236:239], v[86:89]
	v_mfma_f32_16x16x32_f16 v[82:85], v[162:165], v[236:239], v[82:85]
	v_mfma_f32_16x16x32_f16 v[134:137], v[158:161], v[208:211], v[134:137]
	v_mfma_f32_16x16x32_f16 v[130:133], v[166:169], v[208:211], v[130:133]
	v_mfma_f32_16x16x32_f16 v[118:121], v[158:161], v[216:219], v[118:121]
	v_mfma_f32_16x16x32_f16 v[114:117], v[166:169], v[216:219], v[114:117]
	v_mfma_f32_16x16x32_f16 v[102:105], v[158:161], v[232:235], v[102:105]
	v_mfma_f32_16x16x32_f16 v[98:101], v[166:169], v[232:235], v[98:101]
	v_mfma_f32_16x16x32_f16 v[86:89], v[158:161], v[240:243], v[86:89]
	v_mfma_f32_16x16x32_f16 v[82:85], v[166:169], v[240:243], v[82:85]
	v_mfma_f32_16x16x32_f16 v[126:129], v[170:173], v[204:207], v[126:129]
	v_mfma_f32_16x16x32_f16 v[122:125], v[196:199], v[204:207], v[122:125]
	v_mfma_f32_16x16x32_f16 v[110:113], v[170:173], v[212:215], v[110:113]
	v_mfma_f32_16x16x32_f16 v[106:109], v[196:199], v[212:215], v[106:109]
	v_mfma_f32_16x16x32_f16 v[94:97], v[170:173], v[228:231], v[94:97]
	v_mfma_f32_16x16x32_f16 v[90:93], v[196:199], v[228:231], v[90:93]
	v_mfma_f32_16x16x32_f16 v[78:81], v[170:173], v[236:239], v[78:81]
	v_mfma_f32_16x16x32_f16 v[74:77], v[196:199], v[236:239], v[74:77]
	v_mfma_f32_16x16x32_f16 v[126:129], v[188:191], v[208:211], v[126:129]
	v_mfma_f32_16x16x32_f16 v[122:125], v[200:203], v[208:211], v[122:125]
	v_mfma_f32_16x16x32_f16 v[110:113], v[188:191], v[216:219], v[110:113]
	v_mfma_f32_16x16x32_f16 v[106:109], v[200:203], v[216:219], v[106:109]
	v_mfma_f32_16x16x32_f16 v[94:97], v[188:191], v[232:235], v[94:97]
	v_mfma_f32_16x16x32_f16 v[90:93], v[200:203], v[232:235], v[90:93]
	v_mfma_f32_16x16x32_f16 v[78:81], v[188:191], v[240:243], v[78:81]
	v_mfma_f32_16x16x32_f16 v[74:77], v[200:203], v[240:243], v[74:77]
	s_setprio 0
	s_barrier
	s_add_i32 s72, s94, s29
	v_lshl_add_u64 v[192:193], v[192:193], 0, s[34:35]
	s_mov_b32 m0, s72
	ds_read_b128 v[204:207], v187 offset:49152
	ds_read_b128 v[208:211], v187 offset:50176
	ds_read_b128 v[212:215], v187 offset:51200
	ds_read_b128 v[216:219], v187 offset:52224
	ds_read_b128 v[228:231], v187 offset:53248
	ds_read_b128 v[232:235], v187 offset:54272
	ds_read_b128 v[236:239], v187 offset:55296
	ds_read_b128 v[240:243], v187 offset:56320
	global_load_lds_dwordx4 v[192:193], off
	s_add_i32 m0, s72, 0x2000
	s_add_u32 s42, s42, 0x40080
	v_lshl_add_u64 v[192:193], v[244:245], 0, s[34:35]
	s_addc_u32 s43, s43, 0
	s_add_i32 s72, s95, s29
	global_load_lds_dwordx4 v[192:193], off
	v_lshl_add_u64 v[192:193], s[42:43], 0, v[142:143]
	s_mov_b32 m0, s72
	s_nop 0
	global_load_lds_dwordx4 v[192:193], off
	v_lshl_add_u64 v[192:193], s[42:43], 0, v[138:139]
	s_add_i32 m0, s72, 0x2000
	s_nop 0
	global_load_lds_dwordx4 v[192:193], off
	v_lshl_add_u64 v[192:193], v[246:247], 0, s[34:35]
	s_mov_b32 m0, s68
	s_nop 0
	global_load_lds_dwordx4 v[192:193], off
	v_lshl_add_u64 v[192:193], v[248:249], 0, s[34:35]
	s_mov_b32 m0, s69
	s_nop 0
	global_load_lds_dwordx4 v[192:193], off
	s_waitcnt vmcnt(8)
	s_waitcnt lgkmcnt(0)
	s_barrier
	s_setprio 1
	s_waitcnt lgkmcnt(0)
	v_mfma_f32_16x16x32_f16 v[70:73], v[154:157], v[204:207], v[70:73]
	v_mfma_f32_16x16x32_f16 v[66:69], v[162:165], v[204:207], v[66:69]
	v_mfma_f32_16x16x32_f16 v[54:57], v[154:157], v[212:215], v[54:57]
	v_mfma_f32_16x16x32_f16 v[50:53], v[162:165], v[212:215], v[50:53]
	v_mfma_f32_16x16x32_f16 v[38:41], v[154:157], v[228:231], v[38:41]
	v_mfma_f32_16x16x32_f16 v[34:37], v[162:165], v[228:231], v[34:37]
	v_mfma_f32_16x16x32_f16 v[22:25], v[154:157], v[236:239], v[22:25]
	v_mfma_f32_16x16x32_f16 v[18:21], v[162:165], v[236:239], v[18:21]
	v_mfma_f32_16x16x32_f16 v[70:73], v[158:161], v[208:211], v[70:73]
	v_mfma_f32_16x16x32_f16 v[66:69], v[166:169], v[208:211], v[66:69]
	v_mfma_f32_16x16x32_f16 v[54:57], v[158:161], v[216:219], v[54:57]
	v_mfma_f32_16x16x32_f16 v[50:53], v[166:169], v[216:219], v[50:53]
	v_mfma_f32_16x16x32_f16 v[38:41], v[158:161], v[232:235], v[38:41]
	v_mfma_f32_16x16x32_f16 v[34:37], v[166:169], v[232:235], v[34:37]
	v_mfma_f32_16x16x32_f16 v[22:25], v[158:161], v[240:243], v[22:25]
	v_mfma_f32_16x16x32_f16 v[18:21], v[166:169], v[240:243], v[18:21]
	v_mfma_f32_16x16x32_f16 v[62:65], v[170:173], v[204:207], v[62:65]
	v_mfma_f32_16x16x32_f16 v[58:61], v[196:199], v[204:207], v[58:61]
	v_mfma_f32_16x16x32_f16 v[46:49], v[170:173], v[212:215], v[46:49]
	v_mfma_f32_16x16x32_f16 v[42:45], v[196:199], v[212:215], v[42:45]
	v_mfma_f32_16x16x32_f16 v[30:33], v[170:173], v[228:231], v[30:33]
	v_mfma_f32_16x16x32_f16 v[26:29], v[196:199], v[228:231], v[26:29]
	v_mfma_f32_16x16x32_f16 v[14:17], v[170:173], v[236:239], v[14:17]
	v_mfma_f32_16x16x32_f16 v[10:13], v[196:199], v[236:239], v[10:13]
	v_mfma_f32_16x16x32_f16 v[62:65], v[188:191], v[208:211], v[62:65]
	v_mfma_f32_16x16x32_f16 v[58:61], v[200:203], v[208:211], v[58:61]
	v_mfma_f32_16x16x32_f16 v[46:49], v[188:191], v[216:219], v[46:49]
	v_mfma_f32_16x16x32_f16 v[42:45], v[200:203], v[216:219], v[42:45]
	v_mfma_f32_16x16x32_f16 v[30:33], v[188:191], v[232:235], v[30:33]
	v_mfma_f32_16x16x32_f16 v[26:29], v[200:203], v[232:235], v[26:29]
	v_mfma_f32_16x16x32_f16 v[14:17], v[188:191], v[240:243], v[14:17]
	v_mfma_f32_16x16x32_f16 v[10:13], v[200:203], v[240:243], v[10:13]
	s_setprio 0
	s_barrier
	s_add_i32 s91, s91, 2
	s_add_u32 s38, s38, 0x100
	s_addc_u32 s39, s39, 0
	s_add_u32 s78, s78, 0x100
	s_addc_u32 s79, s79, 0
	s_cmp_gt_u32 s91, 13
	s_cbranch_scc0 .LBB0_664
	s_and_b64 vcc, exec, s[48:49]
	s_cbranch_vccz .LBB0_667
	s_barrier
